# gated short conv loop rewritten by hand: all 38 loads of a wave item in flight at once, DPP group reductions (on top of attention v2)
# speedup vs baseline: 1.0146x; 1.0050x over previous
.Latt_done:
.LBB0_867:
	s_cmpk_gt_i32 s66, 0x7ff
	s_cbranch_scc1 .LBB0_877
	s_load_dwordx4 s[4:7], s[0:1], 0x48
	s_load_dwordx2 s[8:9], s[0:1], 0x60
	v_mov_b32_e32 v242, 0x358637bd
	s_mov_b32 s20, s66
	s_lshl_b32 s30, s46, 3
	s_waitcnt lgkmcnt(0)
	s_add_u32 s10, s4, 0x1000
	s_addc_u32 s11, s5, 0
	s_add_u32 s12, s4, 0x2000
	s_addc_u32 s13, s5, 0
.Lcv_item:
	s_and_b32 s24, s20, 1
	s_lshr_b32 s21, s20, 1
	s_lshl_b32 s21, s21, 3
	s_lshl_b32 s25, s24, 11
	v_lshl_add_u32 v240, v234, 5, s25
	s_lshl_b32 s25, s24, 10
	v_lshl_add_u32 v241, v234, 4, s25
	s_and_b32 s26, s21, 0xfff
	s_add_i32 s27, s21, 7
	s_and_b32 s27, s27, 0xfff
	s_mul_i32 s24, s21, 0x1800
	s_mul_hi_u32 s25, s21, 0x1800
	s_add_u32 s28, s50, s24
	s_addc_u32 s29, s51, s25
	s_add_u32 s28, s28, 0x12a00800
	s_addc_u32 s29, s29, 0
	s_lshl_b32 s24, s21, 12
	s_add_u32 s18, s74, s24
	s_addc_u32 s19, s75, 0
	s_add_u32 s18, s18, 0x800
	s_addc_u32 s19, s19, 0
	global_load_dwordx4 v[0:3], v240, s[4:5]
	global_load_dwordx4 v[4:7], v240, s[4:5] offset:16
	global_load_dwordx4 v[8:11], v240, s[10:11]
	global_load_dwordx4 v[12:15], v240, s[10:11] offset:16
	global_load_dwordx4 v[16:19], v240, s[12:13]
	global_load_dwordx4 v[20:23], v240, s[12:13] offset:16
	global_load_dwordx4 v[24:27], v240, s[6:7]
	global_load_dwordx4 v[28:31], v240, s[6:7] offset:16
	global_load_dwordx4 v[32:35], v240, s[8:9]
	global_load_dwordx4 v[36:39], v240, s[8:9] offset:16
	s_cmp_eq_u32 s26, 0
	s_cselect_b32 s24, 0, 0x1800
	s_sub_u32 s16, s28, s24
	s_subb_u32 s17, s29, 0
	global_load_dwordx4 v[40:43], v241, s[16:17]
	global_load_dwordx4 v[44:47], v241, s[16:17] offset:2048
	s_mov_b64 s[16:17], s[28:29]
	s_mov_b64 s[22:23], s[28:29]
	global_load_dwordx4 v[48:51], v241, s[16:17]
	global_load_dwordx4 v[52:55], v241, s[16:17] offset:2048
	s_add_u32 s16, s16, 0x1800
	s_addc_u32 s17, s17, 0
	global_load_dwordx4 v[56:59], v241, s[16:17]
	global_load_dwordx4 v[60:63], v241, s[16:17] offset:2048
	global_load_dwordx4 v[120:123], v241, s[22:23] offset:-2048
	s_add_u32 s22, s22, 0x1800
	s_addc_u32 s23, s23, 0
	s_add_u32 s16, s16, 0x1800
	s_addc_u32 s17, s17, 0
	global_load_dwordx4 v[64:67], v241, s[16:17]
	global_load_dwordx4 v[68:71], v241, s[16:17] offset:2048
	global_load_dwordx4 v[124:127], v241, s[22:23] offset:-2048
	s_add_u32 s22, s22, 0x1800
	s_addc_u32 s23, s23, 0
	s_add_u32 s16, s16, 0x1800
	s_addc_u32 s17, s17, 0
	global_load_dwordx4 v[72:75], v241, s[16:17]
	global_load_dwordx4 v[76:79], v241, s[16:17] offset:2048
	global_load_dwordx4 v[128:131], v241, s[22:23] offset:-2048
	s_add_u32 s22, s22, 0x1800
	s_addc_u32 s23, s23, 0
	s_add_u32 s16, s16, 0x1800
	s_addc_u32 s17, s17, 0
	global_load_dwordx4 v[80:83], v241, s[16:17]
	global_load_dwordx4 v[84:87], v241, s[16:17] offset:2048
	global_load_dwordx4 v[132:135], v241, s[22:23] offset:-2048
	s_add_u32 s22, s22, 0x1800
	s_addc_u32 s23, s23, 0
	s_add_u32 s16, s16, 0x1800
	s_addc_u32 s17, s17, 0
	global_load_dwordx4 v[88:91], v241, s[16:17]
	global_load_dwordx4 v[92:95], v241, s[16:17] offset:2048
	global_load_dwordx4 v[136:139], v241, s[22:23] offset:-2048
	s_add_u32 s22, s22, 0x1800
	s_addc_u32 s23, s23, 0
	s_add_u32 s16, s16, 0x1800
	s_addc_u32 s17, s17, 0
	global_load_dwordx4 v[96:99], v241, s[16:17]
	global_load_dwordx4 v[100:103], v241, s[16:17] offset:2048
	global_load_dwordx4 v[140:143], v241, s[22:23] offset:-2048
	s_add_u32 s22, s22, 0x1800
	s_addc_u32 s23, s23, 0
	s_add_u32 s16, s16, 0x1800
	s_addc_u32 s17, s17, 0
	global_load_dwordx4 v[104:107], v241, s[16:17]
	global_load_dwordx4 v[108:111], v241, s[16:17] offset:2048
	global_load_dwordx4 v[144:147], v241, s[22:23] offset:-2048
	s_add_u32 s22, s22, 0x1800
	s_addc_u32 s23, s23, 0
	s_cmpk_eq_u32 s27, 0xfff
	s_cselect_b32 s24, 0, 0x1800
	s_add_u32 s16, s16, s24
	s_addc_u32 s17, s17, 0
	global_load_dwordx4 v[112:115], v241, s[16:17]
	global_load_dwordx4 v[116:119], v241, s[16:17] offset:2048
	global_load_dwordx4 v[148:151], v241, s[22:23] offset:-2048
	s_mov_b32 s25, 0x800000
	s_waitcnt vmcnt(21)
	s_cmp_lg_u32 s26, 0
	s_cbranch_scc1 .Lcv_pv_ok
	v_mov_b32_e32 v40, 0
	v_mov_b32_e32 v44, 0
	v_mov_b32_e32 v41, 0
	v_mov_b32_e32 v45, 0
	v_mov_b32_e32 v42, 0
	v_mov_b32_e32 v46, 0
	v_mov_b32_e32 v43, 0
	v_mov_b32_e32 v47, 0
.Lcv_pv_ok:
	v_lshlrev_b32_e32 v176, 16, v40
	v_and_b32_e32 v177, 0xffff0000, v40
	v_lshlrev_b32_e32 v184, 16, v44
	v_and_b32_e32 v185, 0xffff0000, v44
	v_lshlrev_b32_e32 v178, 16, v41
	v_and_b32_e32 v179, 0xffff0000, v41
	v_lshlrev_b32_e32 v186, 16, v45
	v_and_b32_e32 v187, 0xffff0000, v45
	v_lshlrev_b32_e32 v180, 16, v42
	v_and_b32_e32 v181, 0xffff0000, v42
	v_lshlrev_b32_e32 v188, 16, v46
	v_and_b32_e32 v189, 0xffff0000, v46
	v_lshlrev_b32_e32 v182, 16, v43
	v_and_b32_e32 v183, 0xffff0000, v43
	v_lshlrev_b32_e32 v190, 16, v47
	v_and_b32_e32 v191, 0xffff0000, v47
	v_pk_mul_f32 v[152:153], v[176:177], v[184:185]
	v_pk_mul_f32 v[154:155], v[178:179], v[186:187]
	v_pk_mul_f32 v[156:157], v[180:181], v[188:189]
	v_pk_mul_f32 v[158:159], v[182:183], v[190:191]
	v_lshlrev_b32_e32 v176, 16, v48
	v_and_b32_e32 v177, 0xffff0000, v48
	v_lshlrev_b32_e32 v184, 16, v52
	v_and_b32_e32 v185, 0xffff0000, v52
	v_lshlrev_b32_e32 v178, 16, v49
	v_and_b32_e32 v179, 0xffff0000, v49
	v_lshlrev_b32_e32 v186, 16, v53
	v_and_b32_e32 v187, 0xffff0000, v53
	v_lshlrev_b32_e32 v180, 16, v50
	v_and_b32_e32 v181, 0xffff0000, v50
	v_lshlrev_b32_e32 v188, 16, v54
	v_and_b32_e32 v189, 0xffff0000, v54
	v_lshlrev_b32_e32 v182, 16, v51
	v_and_b32_e32 v183, 0xffff0000, v51
	v_lshlrev_b32_e32 v190, 16, v55
	v_and_b32_e32 v191, 0xffff0000, v55
	v_pk_mul_f32 v[160:161], v[176:177], v[184:185]
	v_pk_mul_f32 v[162:163], v[178:179], v[186:187]
	v_pk_mul_f32 v[164:165], v[180:181], v[188:189]
	v_pk_mul_f32 v[166:167], v[182:183], v[190:191]
	v_lshlrev_b32_e32 v176, 16, v56
	v_and_b32_e32 v177, 0xffff0000, v56
	v_lshlrev_b32_e32 v184, 16, v60
	v_and_b32_e32 v185, 0xffff0000, v60
	v_lshlrev_b32_e32 v178, 16, v57
	v_and_b32_e32 v179, 0xffff0000, v57
	v_lshlrev_b32_e32 v186, 16, v61
	v_and_b32_e32 v187, 0xffff0000, v61
	v_lshlrev_b32_e32 v180, 16, v58
	v_and_b32_e32 v181, 0xffff0000, v58
	v_lshlrev_b32_e32 v188, 16, v62
	v_and_b32_e32 v189, 0xffff0000, v62
	v_lshlrev_b32_e32 v182, 16, v59
	v_and_b32_e32 v183, 0xffff0000, v59
	v_lshlrev_b32_e32 v190, 16, v63
	v_and_b32_e32 v191, 0xffff0000, v63
	v_pk_mul_f32 v[168:169], v[176:177], v[184:185]
	v_pk_mul_f32 v[170:171], v[178:179], v[186:187]
	v_pk_mul_f32 v[172:173], v[180:181], v[188:189]
	v_pk_mul_f32 v[174:175], v[182:183], v[190:191]
	v_lshlrev_b32_e32 v192, 16, v120
	v_and_b32_e32 v193, 0xffff0000, v120
	v_lshlrev_b32_e32 v194, 16, v121
	v_and_b32_e32 v195, 0xffff0000, v121
	v_lshlrev_b32_e32 v196, 16, v122
	v_and_b32_e32 v197, 0xffff0000, v122
	v_lshlrev_b32_e32 v198, 16, v123
	v_and_b32_e32 v199, 0xffff0000, v123
	v_pk_mul_f32 v[208:209], v[8:9], v[160:161]
	v_pk_mul_f32 v[216:217], v[16:17], v[168:169]
	v_pk_mul_f32 v[210:211], v[10:11], v[162:163]
	v_pk_mul_f32 v[218:219], v[18:19], v[170:171]
	v_pk_mul_f32 v[212:213], v[12:13], v[164:165]
	v_pk_mul_f32 v[220:221], v[20:21], v[172:173]
	v_pk_mul_f32 v[214:215], v[14:15], v[166:167]
	v_pk_mul_f32 v[222:223], v[22:23], v[174:175]
	v_pk_fma_f32 v[200:201], v[0:1], v[152:153], v[208:209]
	v_pk_fma_f32 v[202:203], v[2:3], v[154:155], v[210:211]
	v_pk_fma_f32 v[204:205], v[4:5], v[156:157], v[212:213]
	v_pk_fma_f32 v[206:207], v[6:7], v[158:159], v[214:215]
	v_pk_add_f32 v[200:201], v[200:201], v[216:217]
	v_pk_add_f32 v[202:203], v[202:203], v[218:219]
	v_pk_add_f32 v[204:205], v[204:205], v[220:221]
	v_pk_add_f32 v[206:207], v[206:207], v[222:223]
	v_pk_add_f32 v[200:201], v[24:25], v[200:201]
	v_pk_add_f32 v[202:203], v[26:27], v[202:203]
	v_pk_add_f32 v[204:205], v[28:29], v[204:205]
	v_pk_add_f32 v[206:207], v[30:31], v[206:207]
	v_pk_mul_f32 v[200:201], v[200:201], v[192:193]
	v_pk_mul_f32 v[202:203], v[202:203], v[194:195]
	v_pk_mul_f32 v[204:205], v[204:205], v[196:197]
	v_pk_mul_f32 v[206:207], v[206:207], v[198:199]
	v_pk_mul_f32 v[226:227], v[200:201], v[200:201]
	v_pk_fma_f32 v[226:227], v[202:203], v[202:203], v[226:227]
	v_pk_fma_f32 v[226:227], v[204:205], v[204:205], v[226:227]
	v_pk_fma_f32 v[226:227], v[206:207], v[206:207], v[226:227]
	v_add_f32_e32 v226, v226, v227
	s_nop 1
	v_add_f32_dpp v226, v226, v226 quad_perm:[1,0,3,2] row_mask:0xf bank_mask:0xf
	s_nop 1
	v_add_f32_dpp v226, v226, v226 quad_perm:[2,3,0,1] row_mask:0xf bank_mask:0xf
	s_nop 1
	v_add_f32_dpp v226, v226, v226 row_half_mirror row_mask:0xf bank_mask:0xf
	s_nop 1
	v_add_f32_dpp v226, v226, v226 row_mirror row_mask:0xf bank_mask:0xf
	v_fmamk_f32 v228, v226, 0x3c000000, v242
	v_mul_f32_e32 v230, 0x4b800000, v228
	v_cmp_gt_f32_e32 vcc, s25, v228
	s_nop 1
	v_cndmask_b32_e32 v228, v228, v230, vcc
	v_rsq_f32_e32 v228, v228
	s_nop 0
	v_mul_f32_e32 v230, 0x45800000, v228
	v_cndmask_b32_e32 v228, v228, v230, vcc
	v_pk_mul_f32 v[200:201], v[200:201], v[228:229] op_sel_hi:[1,0]
	v_pk_mul_f32 v[202:203], v[202:203], v[228:229] op_sel_hi:[1,0]
	v_pk_mul_f32 v[204:205], v[204:205], v[228:229] op_sel_hi:[1,0]
	v_pk_mul_f32 v[206:207], v[206:207], v[228:229] op_sel_hi:[1,0]
	v_pk_mul_f32 v[200:201], v[32:33], v[200:201]
	v_pk_mul_f32 v[202:203], v[34:35], v[202:203]
	v_pk_mul_f32 v[204:205], v[36:37], v[204:205]
	v_pk_mul_f32 v[206:207], v[38:39], v[206:207]
	v_cvt_pk_bf16_f32 v208, v200, v201
	v_cvt_pk_bf16_f32 v209, v202, v203
	v_cvt_pk_bf16_f32 v210, v204, v205
	v_cvt_pk_bf16_f32 v211, v206, v207
	global_store_dwordx4 v241, v[208:211], s[18:19]
	s_add_u32 s18, s18, 0x1000
	s_addc_u32 s19, s19, 0
	s_waitcnt vmcnt(18)
	v_lshlrev_b32_e32 v176, 16, v64
	v_and_b32_e32 v177, 0xffff0000, v64
	v_lshlrev_b32_e32 v184, 16, v68
	v_and_b32_e32 v185, 0xffff0000, v68
	v_lshlrev_b32_e32 v178, 16, v65
	v_and_b32_e32 v179, 0xffff0000, v65
	v_lshlrev_b32_e32 v186, 16, v69
	v_and_b32_e32 v187, 0xffff0000, v69
	v_lshlrev_b32_e32 v180, 16, v66
	v_and_b32_e32 v181, 0xffff0000, v66
	v_lshlrev_b32_e32 v188, 16, v70
	v_and_b32_e32 v189, 0xffff0000, v70
	v_lshlrev_b32_e32 v182, 16, v67
	v_and_b32_e32 v183, 0xffff0000, v67
	v_lshlrev_b32_e32 v190, 16, v71
	v_and_b32_e32 v191, 0xffff0000, v71
	v_pk_mul_f32 v[152:153], v[176:177], v[184:185]
	v_pk_mul_f32 v[154:155], v[178:179], v[186:187]
	v_pk_mul_f32 v[156:157], v[180:181], v[188:189]
	v_pk_mul_f32 v[158:159], v[182:183], v[190:191]
	v_lshlrev_b32_e32 v192, 16, v124
	v_and_b32_e32 v193, 0xffff0000, v124
	v_lshlrev_b32_e32 v194, 16, v125
	v_and_b32_e32 v195, 0xffff0000, v125
	v_lshlrev_b32_e32 v196, 16, v126
	v_and_b32_e32 v197, 0xffff0000, v126
	v_lshlrev_b32_e32 v198, 16, v127
	v_and_b32_e32 v199, 0xffff0000, v127
	v_pk_mul_f32 v[208:209], v[8:9], v[168:169]
	v_pk_mul_f32 v[216:217], v[16:17], v[152:153]
	v_pk_mul_f32 v[210:211], v[10:11], v[170:171]
	v_pk_mul_f32 v[218:219], v[18:19], v[154:155]
	v_pk_mul_f32 v[212:213], v[12:13], v[172:173]
	v_pk_mul_f32 v[220:221], v[20:21], v[156:157]
	v_pk_mul_f32 v[214:215], v[14:15], v[174:175]
	v_pk_mul_f32 v[222:223], v[22:23], v[158:159]
	v_pk_fma_f32 v[200:201], v[0:1], v[160:161], v[208:209]
	v_pk_fma_f32 v[202:203], v[2:3], v[162:163], v[210:211]
	v_pk_fma_f32 v[204:205], v[4:5], v[164:165], v[212:213]
	v_pk_fma_f32 v[206:207], v[6:7], v[166:167], v[214:215]
	v_pk_add_f32 v[200:201], v[200:201], v[216:217]
	v_pk_add_f32 v[202:203], v[202:203], v[218:219]
	v_pk_add_f32 v[204:205], v[204:205], v[220:221]
	v_pk_add_f32 v[206:207], v[206:207], v[222:223]
	v_pk_add_f32 v[200:201], v[24:25], v[200:201]
	v_pk_add_f32 v[202:203], v[26:27], v[202:203]
	v_pk_add_f32 v[204:205], v[28:29], v[204:205]
	v_pk_add_f32 v[206:207], v[30:31], v[206:207]
	v_pk_mul_f32 v[200:201], v[200:201], v[192:193]
	v_pk_mul_f32 v[202:203], v[202:203], v[194:195]
	v_pk_mul_f32 v[204:205], v[204:205], v[196:197]
	v_pk_mul_f32 v[206:207], v[206:207], v[198:199]
	v_pk_mul_f32 v[226:227], v[200:201], v[200:201]
	v_pk_fma_f32 v[226:227], v[202:203], v[202:203], v[226:227]
	v_pk_fma_f32 v[226:227], v[204:205], v[204:205], v[226:227]
	v_pk_fma_f32 v[226:227], v[206:207], v[206:207], v[226:227]
	v_add_f32_e32 v226, v226, v227
	s_nop 1
	v_add_f32_dpp v226, v226, v226 quad_perm:[1,0,3,2] row_mask:0xf bank_mask:0xf
	s_nop 1
	v_add_f32_dpp v226, v226, v226 quad_perm:[2,3,0,1] row_mask:0xf bank_mask:0xf
	s_nop 1
	v_add_f32_dpp v226, v226, v226 row_half_mirror row_mask:0xf bank_mask:0xf
	s_nop 1
	v_add_f32_dpp v226, v226, v226 row_mirror row_mask:0xf bank_mask:0xf
	v_fmamk_f32 v228, v226, 0x3c000000, v242
	v_mul_f32_e32 v230, 0x4b800000, v228
	v_cmp_gt_f32_e32 vcc, s25, v228
	s_nop 1
	v_cndmask_b32_e32 v228, v228, v230, vcc
	v_rsq_f32_e32 v228, v228
	s_nop 0
	v_mul_f32_e32 v230, 0x45800000, v228
	v_cndmask_b32_e32 v228, v228, v230, vcc
	v_pk_mul_f32 v[200:201], v[200:201], v[228:229] op_sel_hi:[1,0]
	v_pk_mul_f32 v[202:203], v[202:203], v[228:229] op_sel_hi:[1,0]
	v_pk_mul_f32 v[204:205], v[204:205], v[228:229] op_sel_hi:[1,0]
	v_pk_mul_f32 v[206:207], v[206:207], v[228:229] op_sel_hi:[1,0]
	v_pk_mul_f32 v[200:201], v[32:33], v[200:201]
	v_pk_mul_f32 v[202:203], v[34:35], v[202:203]
	v_pk_mul_f32 v[204:205], v[36:37], v[204:205]
	v_pk_mul_f32 v[206:207], v[38:39], v[206:207]
	v_cvt_pk_bf16_f32 v208, v200, v201
	v_cvt_pk_bf16_f32 v209, v202, v203
	v_cvt_pk_bf16_f32 v210, v204, v205
	v_cvt_pk_bf16_f32 v211, v206, v207
	global_store_dwordx4 v241, v[208:211], s[18:19]
	s_add_u32 s18, s18, 0x1000
	s_addc_u32 s19, s19, 0
	s_waitcnt vmcnt(15)
	v_lshlrev_b32_e32 v176, 16, v72
	v_and_b32_e32 v177, 0xffff0000, v72
	v_lshlrev_b32_e32 v184, 16, v76
	v_and_b32_e32 v185, 0xffff0000, v76
	v_lshlrev_b32_e32 v178, 16, v73
	v_and_b32_e32 v179, 0xffff0000, v73
	v_lshlrev_b32_e32 v186, 16, v77
	v_and_b32_e32 v187, 0xffff0000, v77
	v_lshlrev_b32_e32 v180, 16, v74
	v_and_b32_e32 v181, 0xffff0000, v74
	v_lshlrev_b32_e32 v188, 16, v78
	v_and_b32_e32 v189, 0xffff0000, v78
	v_lshlrev_b32_e32 v182, 16, v75
	v_and_b32_e32 v183, 0xffff0000, v75
	v_lshlrev_b32_e32 v190, 16, v79
	v_and_b32_e32 v191, 0xffff0000, v79
	v_pk_mul_f32 v[160:161], v[176:177], v[184:185]
	v_pk_mul_f32 v[162:163], v[178:179], v[186:187]
	v_pk_mul_f32 v[164:165], v[180:181], v[188:189]
	v_pk_mul_f32 v[166:167], v[182:183], v[190:191]
	v_lshlrev_b32_e32 v192, 16, v128
	v_and_b32_e32 v193, 0xffff0000, v128
	v_lshlrev_b32_e32 v194, 16, v129
	v_and_b32_e32 v195, 0xffff0000, v129
	v_lshlrev_b32_e32 v196, 16, v130
	v_and_b32_e32 v197, 0xffff0000, v130
	v_lshlrev_b32_e32 v198, 16, v131
	v_and_b32_e32 v199, 0xffff0000, v131
	v_pk_mul_f32 v[208:209], v[8:9], v[152:153]
	v_pk_mul_f32 v[216:217], v[16:17], v[160:161]
	v_pk_mul_f32 v[210:211], v[10:11], v[154:155]
	v_pk_mul_f32 v[218:219], v[18:19], v[162:163]
	v_pk_mul_f32 v[212:213], v[12:13], v[156:157]
	v_pk_mul_f32 v[220:221], v[20:21], v[164:165]
	v_pk_mul_f32 v[214:215], v[14:15], v[158:159]
	v_pk_mul_f32 v[222:223], v[22:23], v[166:167]
	v_pk_fma_f32 v[200:201], v[0:1], v[168:169], v[208:209]
	v_pk_fma_f32 v[202:203], v[2:3], v[170:171], v[210:211]
	v_pk_fma_f32 v[204:205], v[4:5], v[172:173], v[212:213]
	v_pk_fma_f32 v[206:207], v[6:7], v[174:175], v[214:215]
	v_pk_add_f32 v[200:201], v[200:201], v[216:217]
	v_pk_add_f32 v[202:203], v[202:203], v[218:219]
	v_pk_add_f32 v[204:205], v[204:205], v[220:221]
	v_pk_add_f32 v[206:207], v[206:207], v[222:223]
	v_pk_add_f32 v[200:201], v[24:25], v[200:201]
	v_pk_add_f32 v[202:203], v[26:27], v[202:203]
	v_pk_add_f32 v[204:205], v[28:29], v[204:205]
	v_pk_add_f32 v[206:207], v[30:31], v[206:207]
	v_pk_mul_f32 v[200:201], v[200:201], v[192:193]
	v_pk_mul_f32 v[202:203], v[202:203], v[194:195]
	v_pk_mul_f32 v[204:205], v[204:205], v[196:197]
	v_pk_mul_f32 v[206:207], v[206:207], v[198:199]
	v_pk_mul_f32 v[226:227], v[200:201], v[200:201]
	v_pk_fma_f32 v[226:227], v[202:203], v[202:203], v[226:227]
	v_pk_fma_f32 v[226:227], v[204:205], v[204:205], v[226:227]
	v_pk_fma_f32 v[226:227], v[206:207], v[206:207], v[226:227]
	v_add_f32_e32 v226, v226, v227
	s_nop 1
	v_add_f32_dpp v226, v226, v226 quad_perm:[1,0,3,2] row_mask:0xf bank_mask:0xf
	s_nop 1
	v_add_f32_dpp v226, v226, v226 quad_perm:[2,3,0,1] row_mask:0xf bank_mask:0xf
	s_nop 1
	v_add_f32_dpp v226, v226, v226 row_half_mirror row_mask:0xf bank_mask:0xf
	s_nop 1
	v_add_f32_dpp v226, v226, v226 row_mirror row_mask:0xf bank_mask:0xf
	v_fmamk_f32 v228, v226, 0x3c000000, v242
	v_mul_f32_e32 v230, 0x4b800000, v228
	v_cmp_gt_f32_e32 vcc, s25, v228
	s_nop 1
	v_cndmask_b32_e32 v228, v228, v230, vcc
	v_rsq_f32_e32 v228, v228
	s_nop 0
	v_mul_f32_e32 v230, 0x45800000, v228
	v_cndmask_b32_e32 v228, v228, v230, vcc
	v_pk_mul_f32 v[200:201], v[200:201], v[228:229] op_sel_hi:[1,0]
	v_pk_mul_f32 v[202:203], v[202:203], v[228:229] op_sel_hi:[1,0]
	v_pk_mul_f32 v[204:205], v[204:205], v[228:229] op_sel_hi:[1,0]
	v_pk_mul_f32 v[206:207], v[206:207], v[228:229] op_sel_hi:[1,0]
	v_pk_mul_f32 v[200:201], v[32:33], v[200:201]
	v_pk_mul_f32 v[202:203], v[34:35], v[202:203]
	v_pk_mul_f32 v[204:205], v[36:37], v[204:205]
	v_pk_mul_f32 v[206:207], v[38:39], v[206:207]
	v_cvt_pk_bf16_f32 v208, v200, v201
	v_cvt_pk_bf16_f32 v209, v202, v203
	v_cvt_pk_bf16_f32 v210, v204, v205
	v_cvt_pk_bf16_f32 v211, v206, v207
	global_store_dwordx4 v241, v[208:211], s[18:19]
	s_add_u32 s18, s18, 0x1000
	s_addc_u32 s19, s19, 0
	s_waitcnt vmcnt(12)
	v_lshlrev_b32_e32 v176, 16, v80
	v_and_b32_e32 v177, 0xffff0000, v80
	v_lshlrev_b32_e32 v184, 16, v84
	v_and_b32_e32 v185, 0xffff0000, v84
	v_lshlrev_b32_e32 v178, 16, v81
	v_and_b32_e32 v179, 0xffff0000, v81
	v_lshlrev_b32_e32 v186, 16, v85
	v_and_b32_e32 v187, 0xffff0000, v85
	v_lshlrev_b32_e32 v180, 16, v82
	v_and_b32_e32 v181, 0xffff0000, v82
	v_lshlrev_b32_e32 v188, 16, v86
	v_and_b32_e32 v189, 0xffff0000, v86
	v_lshlrev_b32_e32 v182, 16, v83
	v_and_b32_e32 v183, 0xffff0000, v83
	v_lshlrev_b32_e32 v190, 16, v87
	v_and_b32_e32 v191, 0xffff0000, v87
	v_pk_mul_f32 v[168:169], v[176:177], v[184:185]
	v_pk_mul_f32 v[170:171], v[178:179], v[186:187]
	v_pk_mul_f32 v[172:173], v[180:181], v[188:189]
	v_pk_mul_f32 v[174:175], v[182:183], v[190:191]
	v_lshlrev_b32_e32 v192, 16, v132
	v_and_b32_e32 v193, 0xffff0000, v132
	v_lshlrev_b32_e32 v194, 16, v133
	v_and_b32_e32 v195, 0xffff0000, v133
	v_lshlrev_b32_e32 v196, 16, v134
	v_and_b32_e32 v197, 0xffff0000, v134
	v_lshlrev_b32_e32 v198, 16, v135
	v_and_b32_e32 v199, 0xffff0000, v135
	v_pk_mul_f32 v[208:209], v[8:9], v[160:161]
	v_pk_mul_f32 v[216:217], v[16:17], v[168:169]
	v_pk_mul_f32 v[210:211], v[10:11], v[162:163]
	v_pk_mul_f32 v[218:219], v[18:19], v[170:171]
	v_pk_mul_f32 v[212:213], v[12:13], v[164:165]
	v_pk_mul_f32 v[220:221], v[20:21], v[172:173]
	v_pk_mul_f32 v[214:215], v[14:15], v[166:167]
	v_pk_mul_f32 v[222:223], v[22:23], v[174:175]
	v_pk_fma_f32 v[200:201], v[0:1], v[152:153], v[208:209]
	v_pk_fma_f32 v[202:203], v[2:3], v[154:155], v[210:211]
	v_pk_fma_f32 v[204:205], v[4:5], v[156:157], v[212:213]
	v_pk_fma_f32 v[206:207], v[6:7], v[158:159], v[214:215]
	v_pk_add_f32 v[200:201], v[200:201], v[216:217]
	v_pk_add_f32 v[202:203], v[202:203], v[218:219]
	v_pk_add_f32 v[204:205], v[204:205], v[220:221]
	v_pk_add_f32 v[206:207], v[206:207], v[222:223]
	v_pk_add_f32 v[200:201], v[24:25], v[200:201]
	v_pk_add_f32 v[202:203], v[26:27], v[202:203]
	v_pk_add_f32 v[204:205], v[28:29], v[204:205]
	v_pk_add_f32 v[206:207], v[30:31], v[206:207]
	v_pk_mul_f32 v[200:201], v[200:201], v[192:193]
	v_pk_mul_f32 v[202:203], v[202:203], v[194:195]
	v_pk_mul_f32 v[204:205], v[204:205], v[196:197]
	v_pk_mul_f32 v[206:207], v[206:207], v[198:199]
	v_pk_mul_f32 v[226:227], v[200:201], v[200:201]
	v_pk_fma_f32 v[226:227], v[202:203], v[202:203], v[226:227]
	v_pk_fma_f32 v[226:227], v[204:205], v[204:205], v[226:227]
	v_pk_fma_f32 v[226:227], v[206:207], v[206:207], v[226:227]
	v_add_f32_e32 v226, v226, v227
	s_nop 1
	v_add_f32_dpp v226, v226, v226 quad_perm:[1,0,3,2] row_mask:0xf bank_mask:0xf
	s_nop 1
	v_add_f32_dpp v226, v226, v226 quad_perm:[2,3,0,1] row_mask:0xf bank_mask:0xf
	s_nop 1
	v_add_f32_dpp v226, v226, v226 row_half_mirror row_mask:0xf bank_mask:0xf
	s_nop 1
	v_add_f32_dpp v226, v226, v226 row_mirror row_mask:0xf bank_mask:0xf
	v_fmamk_f32 v228, v226, 0x3c000000, v242
	v_mul_f32_e32 v230, 0x4b800000, v228
	v_cmp_gt_f32_e32 vcc, s25, v228
	s_nop 1
	v_cndmask_b32_e32 v228, v228, v230, vcc
	v_rsq_f32_e32 v228, v228
	s_nop 0
	v_mul_f32_e32 v230, 0x45800000, v228
	v_cndmask_b32_e32 v228, v228, v230, vcc
	v_pk_mul_f32 v[200:201], v[200:201], v[228:229] op_sel_hi:[1,0]
	v_pk_mul_f32 v[202:203], v[202:203], v[228:229] op_sel_hi:[1,0]
	v_pk_mul_f32 v[204:205], v[204:205], v[228:229] op_sel_hi:[1,0]
	v_pk_mul_f32 v[206:207], v[206:207], v[228:229] op_sel_hi:[1,0]
	v_pk_mul_f32 v[200:201], v[32:33], v[200:201]
	v_pk_mul_f32 v[202:203], v[34:35], v[202:203]
	v_pk_mul_f32 v[204:205], v[36:37], v[204:205]
	v_pk_mul_f32 v[206:207], v[38:39], v[206:207]
	v_cvt_pk_bf16_f32 v208, v200, v201
	v_cvt_pk_bf16_f32 v209, v202, v203
	v_cvt_pk_bf16_f32 v210, v204, v205
	v_cvt_pk_bf16_f32 v211, v206, v207
	global_store_dwordx4 v241, v[208:211], s[18:19]
	s_add_u32 s18, s18, 0x1000
	s_addc_u32 s19, s19, 0
	s_waitcnt vmcnt(9)
	v_lshlrev_b32_e32 v176, 16, v88
	v_and_b32_e32 v177, 0xffff0000, v88
	v_lshlrev_b32_e32 v184, 16, v92
	v_and_b32_e32 v185, 0xffff0000, v92
	v_lshlrev_b32_e32 v178, 16, v89
	v_and_b32_e32 v179, 0xffff0000, v89
	v_lshlrev_b32_e32 v186, 16, v93
	v_and_b32_e32 v187, 0xffff0000, v93
	v_lshlrev_b32_e32 v180, 16, v90
	v_and_b32_e32 v181, 0xffff0000, v90
	v_lshlrev_b32_e32 v188, 16, v94
	v_and_b32_e32 v189, 0xffff0000, v94
	v_lshlrev_b32_e32 v182, 16, v91
	v_and_b32_e32 v183, 0xffff0000, v91
	v_lshlrev_b32_e32 v190, 16, v95
	v_and_b32_e32 v191, 0xffff0000, v95
	v_pk_mul_f32 v[152:153], v[176:177], v[184:185]
	v_pk_mul_f32 v[154:155], v[178:179], v[186:187]
	v_pk_mul_f32 v[156:157], v[180:181], v[188:189]
	v_pk_mul_f32 v[158:159], v[182:183], v[190:191]
	v_lshlrev_b32_e32 v192, 16, v136
	v_and_b32_e32 v193, 0xffff0000, v136
	v_lshlrev_b32_e32 v194, 16, v137
	v_and_b32_e32 v195, 0xffff0000, v137
	v_lshlrev_b32_e32 v196, 16, v138
	v_and_b32_e32 v197, 0xffff0000, v138
	v_lshlrev_b32_e32 v198, 16, v139
	v_and_b32_e32 v199, 0xffff0000, v139
	v_pk_mul_f32 v[208:209], v[8:9], v[168:169]
	v_pk_mul_f32 v[216:217], v[16:17], v[152:153]
	v_pk_mul_f32 v[210:211], v[10:11], v[170:171]
	v_pk_mul_f32 v[218:219], v[18:19], v[154:155]
	v_pk_mul_f32 v[212:213], v[12:13], v[172:173]
	v_pk_mul_f32 v[220:221], v[20:21], v[156:157]
	v_pk_mul_f32 v[214:215], v[14:15], v[174:175]
	v_pk_mul_f32 v[222:223], v[22:23], v[158:159]
	v_pk_fma_f32 v[200:201], v[0:1], v[160:161], v[208:209]
	v_pk_fma_f32 v[202:203], v[2:3], v[162:163], v[210:211]
	v_pk_fma_f32 v[204:205], v[4:5], v[164:165], v[212:213]
	v_pk_fma_f32 v[206:207], v[6:7], v[166:167], v[214:215]
	v_pk_add_f32 v[200:201], v[200:201], v[216:217]
	v_pk_add_f32 v[202:203], v[202:203], v[218:219]
	v_pk_add_f32 v[204:205], v[204:205], v[220:221]
	v_pk_add_f32 v[206:207], v[206:207], v[222:223]
	v_pk_add_f32 v[200:201], v[24:25], v[200:201]
	v_pk_add_f32 v[202:203], v[26:27], v[202:203]
	v_pk_add_f32 v[204:205], v[28:29], v[204:205]
	v_pk_add_f32 v[206:207], v[30:31], v[206:207]
	v_pk_mul_f32 v[200:201], v[200:201], v[192:193]
	v_pk_mul_f32 v[202:203], v[202:203], v[194:195]
	v_pk_mul_f32 v[204:205], v[204:205], v[196:197]
	v_pk_mul_f32 v[206:207], v[206:207], v[198:199]
	v_pk_mul_f32 v[226:227], v[200:201], v[200:201]
	v_pk_fma_f32 v[226:227], v[202:203], v[202:203], v[226:227]
	v_pk_fma_f32 v[226:227], v[204:205], v[204:205], v[226:227]
	v_pk_fma_f32 v[226:227], v[206:207], v[206:207], v[226:227]
	v_add_f32_e32 v226, v226, v227
	s_nop 1
	v_add_f32_dpp v226, v226, v226 quad_perm:[1,0,3,2] row_mask:0xf bank_mask:0xf
	s_nop 1
	v_add_f32_dpp v226, v226, v226 quad_perm:[2,3,0,1] row_mask:0xf bank_mask:0xf
	s_nop 1
	v_add_f32_dpp v226, v226, v226 row_half_mirror row_mask:0xf bank_mask:0xf
	s_nop 1
	v_add_f32_dpp v226, v226, v226 row_mirror row_mask:0xf bank_mask:0xf
	v_fmamk_f32 v228, v226, 0x3c000000, v242
	v_mul_f32_e32 v230, 0x4b800000, v228
	v_cmp_gt_f32_e32 vcc, s25, v228
	s_nop 1
	v_cndmask_b32_e32 v228, v228, v230, vcc
	v_rsq_f32_e32 v228, v228
	s_nop 0
	v_mul_f32_e32 v230, 0x45800000, v228
	v_cndmask_b32_e32 v228, v228, v230, vcc
	v_pk_mul_f32 v[200:201], v[200:201], v[228:229] op_sel_hi:[1,0]
	v_pk_mul_f32 v[202:203], v[202:203], v[228:229] op_sel_hi:[1,0]
	v_pk_mul_f32 v[204:205], v[204:205], v[228:229] op_sel_hi:[1,0]
	v_pk_mul_f32 v[206:207], v[206:207], v[228:229] op_sel_hi:[1,0]
	v_pk_mul_f32 v[200:201], v[32:33], v[200:201]
	v_pk_mul_f32 v[202:203], v[34:35], v[202:203]
	v_pk_mul_f32 v[204:205], v[36:37], v[204:205]
	v_pk_mul_f32 v[206:207], v[38:39], v[206:207]
	v_cvt_pk_bf16_f32 v208, v200, v201
	v_cvt_pk_bf16_f32 v209, v202, v203
	v_cvt_pk_bf16_f32 v210, v204, v205
	v_cvt_pk_bf16_f32 v211, v206, v207
	global_store_dwordx4 v241, v[208:211], s[18:19]
	s_add_u32 s18, s18, 0x1000
	s_addc_u32 s19, s19, 0
	s_waitcnt vmcnt(6)
	v_lshlrev_b32_e32 v176, 16, v96
	v_and_b32_e32 v177, 0xffff0000, v96
	v_lshlrev_b32_e32 v184, 16, v100
	v_and_b32_e32 v185, 0xffff0000, v100
	v_lshlrev_b32_e32 v178, 16, v97
	v_and_b32_e32 v179, 0xffff0000, v97
	v_lshlrev_b32_e32 v186, 16, v101
	v_and_b32_e32 v187, 0xffff0000, v101
	v_lshlrev_b32_e32 v180, 16, v98
	v_and_b32_e32 v181, 0xffff0000, v98
	v_lshlrev_b32_e32 v188, 16, v102
	v_and_b32_e32 v189, 0xffff0000, v102
	v_lshlrev_b32_e32 v182, 16, v99
	v_and_b32_e32 v183, 0xffff0000, v99
	v_lshlrev_b32_e32 v190, 16, v103
	v_and_b32_e32 v191, 0xffff0000, v103
	v_pk_mul_f32 v[160:161], v[176:177], v[184:185]
	v_pk_mul_f32 v[162:163], v[178:179], v[186:187]
	v_pk_mul_f32 v[164:165], v[180:181], v[188:189]
	v_pk_mul_f32 v[166:167], v[182:183], v[190:191]
	v_lshlrev_b32_e32 v192, 16, v140
	v_and_b32_e32 v193, 0xffff0000, v140
	v_lshlrev_b32_e32 v194, 16, v141
	v_and_b32_e32 v195, 0xffff0000, v141
	v_lshlrev_b32_e32 v196, 16, v142
	v_and_b32_e32 v197, 0xffff0000, v142
	v_lshlrev_b32_e32 v198, 16, v143
	v_and_b32_e32 v199, 0xffff0000, v143
	v_pk_mul_f32 v[208:209], v[8:9], v[152:153]
	v_pk_mul_f32 v[216:217], v[16:17], v[160:161]
	v_pk_mul_f32 v[210:211], v[10:11], v[154:155]
	v_pk_mul_f32 v[218:219], v[18:19], v[162:163]
	v_pk_mul_f32 v[212:213], v[12:13], v[156:157]
	v_pk_mul_f32 v[220:221], v[20:21], v[164:165]
	v_pk_mul_f32 v[214:215], v[14:15], v[158:159]
	v_pk_mul_f32 v[222:223], v[22:23], v[166:167]
	v_pk_fma_f32 v[200:201], v[0:1], v[168:169], v[208:209]
	v_pk_fma_f32 v[202:203], v[2:3], v[170:171], v[210:211]
	v_pk_fma_f32 v[204:205], v[4:5], v[172:173], v[212:213]
	v_pk_fma_f32 v[206:207], v[6:7], v[174:175], v[214:215]
	v_pk_add_f32 v[200:201], v[200:201], v[216:217]
	v_pk_add_f32 v[202:203], v[202:203], v[218:219]
	v_pk_add_f32 v[204:205], v[204:205], v[220:221]
	v_pk_add_f32 v[206:207], v[206:207], v[222:223]
	v_pk_add_f32 v[200:201], v[24:25], v[200:201]
	v_pk_add_f32 v[202:203], v[26:27], v[202:203]
	v_pk_add_f32 v[204:205], v[28:29], v[204:205]
	v_pk_add_f32 v[206:207], v[30:31], v[206:207]
	v_pk_mul_f32 v[200:201], v[200:201], v[192:193]
	v_pk_mul_f32 v[202:203], v[202:203], v[194:195]
	v_pk_mul_f32 v[204:205], v[204:205], v[196:197]
	v_pk_mul_f32 v[206:207], v[206:207], v[198:199]
	v_pk_mul_f32 v[226:227], v[200:201], v[200:201]
	v_pk_fma_f32 v[226:227], v[202:203], v[202:203], v[226:227]
	v_pk_fma_f32 v[226:227], v[204:205], v[204:205], v[226:227]
	v_pk_fma_f32 v[226:227], v[206:207], v[206:207], v[226:227]
	v_add_f32_e32 v226, v226, v227
	s_nop 1
	v_add_f32_dpp v226, v226, v226 quad_perm:[1,0,3,2] row_mask:0xf bank_mask:0xf
	s_nop 1
	v_add_f32_dpp v226, v226, v226 quad_perm:[2,3,0,1] row_mask:0xf bank_mask:0xf
	s_nop 1
	v_add_f32_dpp v226, v226, v226 row_half_mirror row_mask:0xf bank_mask:0xf
	s_nop 1
	v_add_f32_dpp v226, v226, v226 row_mirror row_mask:0xf bank_mask:0xf
	v_fmamk_f32 v228, v226, 0x3c000000, v242
	v_mul_f32_e32 v230, 0x4b800000, v228
	v_cmp_gt_f32_e32 vcc, s25, v228
	s_nop 1
	v_cndmask_b32_e32 v228, v228, v230, vcc
	v_rsq_f32_e32 v228, v228
	s_nop 0
	v_mul_f32_e32 v230, 0x45800000, v228
	v_cndmask_b32_e32 v228, v228, v230, vcc
	v_pk_mul_f32 v[200:201], v[200:201], v[228:229] op_sel_hi:[1,0]
	v_pk_mul_f32 v[202:203], v[202:203], v[228:229] op_sel_hi:[1,0]
	v_pk_mul_f32 v[204:205], v[204:205], v[228:229] op_sel_hi:[1,0]
	v_pk_mul_f32 v[206:207], v[206:207], v[228:229] op_sel_hi:[1,0]
	v_pk_mul_f32 v[200:201], v[32:33], v[200:201]
	v_pk_mul_f32 v[202:203], v[34:35], v[202:203]
	v_pk_mul_f32 v[204:205], v[36:37], v[204:205]
	v_pk_mul_f32 v[206:207], v[38:39], v[206:207]
	v_cvt_pk_bf16_f32 v208, v200, v201
	v_cvt_pk_bf16_f32 v209, v202, v203
	v_cvt_pk_bf16_f32 v210, v204, v205
	v_cvt_pk_bf16_f32 v211, v206, v207
	global_store_dwordx4 v241, v[208:211], s[18:19]
	s_add_u32 s18, s18, 0x1000
	s_addc_u32 s19, s19, 0
	s_waitcnt vmcnt(3)
	v_lshlrev_b32_e32 v176, 16, v104
	v_and_b32_e32 v177, 0xffff0000, v104
	v_lshlrev_b32_e32 v184, 16, v108
	v_and_b32_e32 v185, 0xffff0000, v108
	v_lshlrev_b32_e32 v178, 16, v105
	v_and_b32_e32 v179, 0xffff0000, v105
	v_lshlrev_b32_e32 v186, 16, v109
	v_and_b32_e32 v187, 0xffff0000, v109
	v_lshlrev_b32_e32 v180, 16, v106
	v_and_b32_e32 v181, 0xffff0000, v106
	v_lshlrev_b32_e32 v188, 16, v110
	v_and_b32_e32 v189, 0xffff0000, v110
	v_lshlrev_b32_e32 v182, 16, v107
	v_and_b32_e32 v183, 0xffff0000, v107
	v_lshlrev_b32_e32 v190, 16, v111
	v_and_b32_e32 v191, 0xffff0000, v111
	v_pk_mul_f32 v[168:169], v[176:177], v[184:185]
	v_pk_mul_f32 v[170:171], v[178:179], v[186:187]
	v_pk_mul_f32 v[172:173], v[180:181], v[188:189]
	v_pk_mul_f32 v[174:175], v[182:183], v[190:191]
	v_lshlrev_b32_e32 v192, 16, v144
	v_and_b32_e32 v193, 0xffff0000, v144
	v_lshlrev_b32_e32 v194, 16, v145
	v_and_b32_e32 v195, 0xffff0000, v145
	v_lshlrev_b32_e32 v196, 16, v146
	v_and_b32_e32 v197, 0xffff0000, v146
	v_lshlrev_b32_e32 v198, 16, v147
	v_and_b32_e32 v199, 0xffff0000, v147
	v_pk_mul_f32 v[208:209], v[8:9], v[160:161]
	v_pk_mul_f32 v[216:217], v[16:17], v[168:169]
	v_pk_mul_f32 v[210:211], v[10:11], v[162:163]
	v_pk_mul_f32 v[218:219], v[18:19], v[170:171]
	v_pk_mul_f32 v[212:213], v[12:13], v[164:165]
	v_pk_mul_f32 v[220:221], v[20:21], v[172:173]
	v_pk_mul_f32 v[214:215], v[14:15], v[166:167]
	v_pk_mul_f32 v[222:223], v[22:23], v[174:175]
	v_pk_fma_f32 v[200:201], v[0:1], v[152:153], v[208:209]
	v_pk_fma_f32 v[202:203], v[2:3], v[154:155], v[210:211]
	v_pk_fma_f32 v[204:205], v[4:5], v[156:157], v[212:213]
	v_pk_fma_f32 v[206:207], v[6:7], v[158:159], v[214:215]
	v_pk_add_f32 v[200:201], v[200:201], v[216:217]
	v_pk_add_f32 v[202:203], v[202:203], v[218:219]
	v_pk_add_f32 v[204:205], v[204:205], v[220:221]
	v_pk_add_f32 v[206:207], v[206:207], v[222:223]
	v_pk_add_f32 v[200:201], v[24:25], v[200:201]
	v_pk_add_f32 v[202:203], v[26:27], v[202:203]
	v_pk_add_f32 v[204:205], v[28:29], v[204:205]
	v_pk_add_f32 v[206:207], v[30:31], v[206:207]
	v_pk_mul_f32 v[200:201], v[200:201], v[192:193]
	v_pk_mul_f32 v[202:203], v[202:203], v[194:195]
	v_pk_mul_f32 v[204:205], v[204:205], v[196:197]
	v_pk_mul_f32 v[206:207], v[206:207], v[198:199]
	v_pk_mul_f32 v[226:227], v[200:201], v[200:201]
	v_pk_fma_f32 v[226:227], v[202:203], v[202:203], v[226:227]
	v_pk_fma_f32 v[226:227], v[204:205], v[204:205], v[226:227]
	v_pk_fma_f32 v[226:227], v[206:207], v[206:207], v[226:227]
	v_add_f32_e32 v226, v226, v227
	s_nop 1
	v_add_f32_dpp v226, v226, v226 quad_perm:[1,0,3,2] row_mask:0xf bank_mask:0xf
	s_nop 1
	v_add_f32_dpp v226, v226, v226 quad_perm:[2,3,0,1] row_mask:0xf bank_mask:0xf
	s_nop 1
	v_add_f32_dpp v226, v226, v226 row_half_mirror row_mask:0xf bank_mask:0xf
	s_nop 1
	v_add_f32_dpp v226, v226, v226 row_mirror row_mask:0xf bank_mask:0xf
	v_fmamk_f32 v228, v226, 0x3c000000, v242
	v_mul_f32_e32 v230, 0x4b800000, v228
	v_cmp_gt_f32_e32 vcc, s25, v228
	s_nop 1
	v_cndmask_b32_e32 v228, v228, v230, vcc
	v_rsq_f32_e32 v228, v228
	s_nop 0
	v_mul_f32_e32 v230, 0x45800000, v228
	v_cndmask_b32_e32 v228, v228, v230, vcc
	v_pk_mul_f32 v[200:201], v[200:201], v[228:229] op_sel_hi:[1,0]
	v_pk_mul_f32 v[202:203], v[202:203], v[228:229] op_sel_hi:[1,0]
	v_pk_mul_f32 v[204:205], v[204:205], v[228:229] op_sel_hi:[1,0]
	v_pk_mul_f32 v[206:207], v[206:207], v[228:229] op_sel_hi:[1,0]
	v_pk_mul_f32 v[200:201], v[32:33], v[200:201]
	v_pk_mul_f32 v[202:203], v[34:35], v[202:203]
	v_pk_mul_f32 v[204:205], v[36:37], v[204:205]
	v_pk_mul_f32 v[206:207], v[38:39], v[206:207]
	v_cvt_pk_bf16_f32 v208, v200, v201
	v_cvt_pk_bf16_f32 v209, v202, v203
	v_cvt_pk_bf16_f32 v210, v204, v205
	v_cvt_pk_bf16_f32 v211, v206, v207
	global_store_dwordx4 v241, v[208:211], s[18:19]
	s_add_u32 s18, s18, 0x1000
	s_addc_u32 s19, s19, 0
	s_waitcnt vmcnt(0)
	s_cmpk_lg_u32 s27, 0xfff
	s_cbranch_scc1 .Lcv_nv_ok
	v_mov_b32_e32 v112, 0
	v_mov_b32_e32 v116, 0
	v_mov_b32_e32 v113, 0
	v_mov_b32_e32 v117, 0
	v_mov_b32_e32 v114, 0
	v_mov_b32_e32 v118, 0
	v_mov_b32_e32 v115, 0
	v_mov_b32_e32 v119, 0
.Lcv_nv_ok:
	v_lshlrev_b32_e32 v176, 16, v112
	v_and_b32_e32 v177, 0xffff0000, v112
	v_lshlrev_b32_e32 v184, 16, v116
	v_and_b32_e32 v185, 0xffff0000, v116
	v_lshlrev_b32_e32 v178, 16, v113
	v_and_b32_e32 v179, 0xffff0000, v113
	v_lshlrev_b32_e32 v186, 16, v117
	v_and_b32_e32 v187, 0xffff0000, v117
	v_lshlrev_b32_e32 v180, 16, v114
	v_and_b32_e32 v181, 0xffff0000, v114
	v_lshlrev_b32_e32 v188, 16, v118
	v_and_b32_e32 v189, 0xffff0000, v118
	v_lshlrev_b32_e32 v182, 16, v115
	v_and_b32_e32 v183, 0xffff0000, v115
	v_lshlrev_b32_e32 v190, 16, v119
	v_and_b32_e32 v191, 0xffff0000, v119
	v_pk_mul_f32 v[152:153], v[176:177], v[184:185]
	v_pk_mul_f32 v[154:155], v[178:179], v[186:187]
	v_pk_mul_f32 v[156:157], v[180:181], v[188:189]
	v_pk_mul_f32 v[158:159], v[182:183], v[190:191]
	v_lshlrev_b32_e32 v192, 16, v148
	v_and_b32_e32 v193, 0xffff0000, v148
	v_lshlrev_b32_e32 v194, 16, v149
	v_and_b32_e32 v195, 0xffff0000, v149
	v_lshlrev_b32_e32 v196, 16, v150
	v_and_b32_e32 v197, 0xffff0000, v150
	v_lshlrev_b32_e32 v198, 16, v151
	v_and_b32_e32 v199, 0xffff0000, v151
	v_pk_mul_f32 v[208:209], v[8:9], v[168:169]
	v_pk_mul_f32 v[216:217], v[16:17], v[152:153]
	v_pk_mul_f32 v[210:211], v[10:11], v[170:171]
	v_pk_mul_f32 v[218:219], v[18:19], v[154:155]
	v_pk_mul_f32 v[212:213], v[12:13], v[172:173]
	v_pk_mul_f32 v[220:221], v[20:21], v[156:157]
	v_pk_mul_f32 v[214:215], v[14:15], v[174:175]
	v_pk_mul_f32 v[222:223], v[22:23], v[158:159]
	v_pk_fma_f32 v[200:201], v[0:1], v[160:161], v[208:209]
	v_pk_fma_f32 v[202:203], v[2:3], v[162:163], v[210:211]
	v_pk_fma_f32 v[204:205], v[4:5], v[164:165], v[212:213]
	v_pk_fma_f32 v[206:207], v[6:7], v[166:167], v[214:215]
	v_pk_add_f32 v[200:201], v[200:201], v[216:217]
	v_pk_add_f32 v[202:203], v[202:203], v[218:219]
	v_pk_add_f32 v[204:205], v[204:205], v[220:221]
	v_pk_add_f32 v[206:207], v[206:207], v[222:223]
	v_pk_add_f32 v[200:201], v[24:25], v[200:201]
	v_pk_add_f32 v[202:203], v[26:27], v[202:203]
	v_pk_add_f32 v[204:205], v[28:29], v[204:205]
	v_pk_add_f32 v[206:207], v[30:31], v[206:207]
	v_pk_mul_f32 v[200:201], v[200:201], v[192:193]
	v_pk_mul_f32 v[202:203], v[202:203], v[194:195]
	v_pk_mul_f32 v[204:205], v[204:205], v[196:197]
	v_pk_mul_f32 v[206:207], v[206:207], v[198:199]
	v_pk_mul_f32 v[226:227], v[200:201], v[200:201]
	v_pk_fma_f32 v[226:227], v[202:203], v[202:203], v[226:227]
	v_pk_fma_f32 v[226:227], v[204:205], v[204:205], v[226:227]
	v_pk_fma_f32 v[226:227], v[206:207], v[206:207], v[226:227]
	v_add_f32_e32 v226, v226, v227
	s_nop 1
	v_add_f32_dpp v226, v226, v226 quad_perm:[1,0,3,2] row_mask:0xf bank_mask:0xf
	s_nop 1
	v_add_f32_dpp v226, v226, v226 quad_perm:[2,3,0,1] row_mask:0xf bank_mask:0xf
	s_nop 1
	v_add_f32_dpp v226, v226, v226 row_half_mirror row_mask:0xf bank_mask:0xf
	s_nop 1
	v_add_f32_dpp v226, v226, v226 row_mirror row_mask:0xf bank_mask:0xf
	v_fmamk_f32 v228, v226, 0x3c000000, v242
	v_mul_f32_e32 v230, 0x4b800000, v228
	v_cmp_gt_f32_e32 vcc, s25, v228
	s_nop 1
	v_cndmask_b32_e32 v228, v228, v230, vcc
	v_rsq_f32_e32 v228, v228
	s_nop 0
	v_mul_f32_e32 v230, 0x45800000, v228
	v_cndmask_b32_e32 v228, v228, v230, vcc
	v_pk_mul_f32 v[200:201], v[200:201], v[228:229] op_sel_hi:[1,0]
	v_pk_mul_f32 v[202:203], v[202:203], v[228:229] op_sel_hi:[1,0]
	v_pk_mul_f32 v[204:205], v[204:205], v[228:229] op_sel_hi:[1,0]
	v_pk_mul_f32 v[206:207], v[206:207], v[228:229] op_sel_hi:[1,0]
	v_pk_mul_f32 v[200:201], v[32:33], v[200:201]
	v_pk_mul_f32 v[202:203], v[34:35], v[202:203]
	v_pk_mul_f32 v[204:205], v[36:37], v[204:205]
	v_pk_mul_f32 v[206:207], v[38:39], v[206:207]
	v_cvt_pk_bf16_f32 v208, v200, v201
	v_cvt_pk_bf16_f32 v209, v202, v203
	v_cvt_pk_bf16_f32 v210, v204, v205
	v_cvt_pk_bf16_f32 v211, v206, v207
	global_store_dwordx4 v241, v[208:211], s[18:19]
	s_add_i32 s20, s20, s30
	s_cmpk_lt_i32 s20, 0x800
	s_cbranch_scc1 .Lcv_item
